# stack1 + rows phase: LN gamma/beta served from a per-wave LDS copy made once before the row loop (was 8 serial global load->vmcnt(0) steps per row); per-step waits lgkmcnt(0)
# speedup vs baseline: 1.0212x; 1.0084x over previous
; __device__ __forceinline__ void phase_rows(const Ctx& c, int l) {
;     ...
;     const float* src = (l == 0) ? c.inp(IN_X) : c.out;
;     bf16_t* XB = (bf16_t*)(c.ws + WS_XB);
;     float* flog = (float*)(c.ws + WS_FLOG);
;     for (int m0 = gw; m0 < MTOK; m0 += 2 * NGW) {
;     ...
;             const f32x4* gp = (const f32x4*)(c.inp(IN_LNG) + (size_t)(l - 1) * DM) + lane; const f32x4* bp = (const f32x4*)(c.inp(IN_LNB) + (size_t)(l - 1) * DM) + lane;
.LBB0_484:
	v_readlane_b32 s16, v253, 4
	v_readlane_b32 s17, v253, 5
	s_cmp_gt_i32 s16, 6
	s_cselect_b64 s[48:49], -1, 0
	s_sub_i32 s0, s16, 28
	v_readlane_b32 s16, v253, 0
	v_readlane_b32 s17, v253, 1
	s_load_dwordx4 s[40:43], s[16:17], 0xa8
	s_add_i32 s34, s80, -1
	v_lshlrev_b32_e32 v96, 4, v200
	s_lshl_b64 s[22:23], s[34:35], 10
	s_waitcnt lgkmcnt(0)
	v_lshl_add_u64 v[174:175], s[38:39], 0, v[96:97]
	s_cmp_lt_u32 s0, 7
	v_cmp_eq_u32_e64 s[38:39], 0, v200
	s_waitcnt vmcnt(0)
	v_lshlrev_b32_e32 v138, 3, v200
	v_mov_b32_e32 v139, v97
	v_mov_b32_e32 v201, v97
	s_cselect_b64 s[50:51], -1, 0
	s_and_b64 s[52:53], s[44:45], s[38:39]
	v_lshl_add_u64 v[176:177], s[82:83], 0, v[138:139]
	v_lshl_add_u64 v[178:179], s[40:41], 0, v[96:97]
	s_andn2_b64 vcc, exec, s[48:49]
	s_cbranch_vccnz .Lrows_lds_skip
	s_load_dwordx2 s[98:99], s[12:13], 0x98
	s_load_dwordx2 s[100:101], s[12:13], 0xa0
	v_lshrrev_b32_e32 v251, 6, v212
	v_lshlrev_b32_e32 v251, 14, v251
	v_lshl_add_u32 v251, v200, 4, v251
	s_lshl_b64 s[16:17], s[22:23], 2
	s_waitcnt lgkmcnt(0)
	s_add_u32 s98, s98, s16
	s_addc_u32 s99, s99, s17
	s_add_u32 s100, s100, s16
	s_addc_u32 s101, s101, s17
	global_load_dwordx4 v[238:241], v96, s[98:99]
	global_load_dwordx4 v[242:245], v96, s[98:99] offset:1024
	global_load_dwordx4 v[246:249], v96, s[98:99] offset:2048
	global_load_dwordx4 v[206:209], v96, s[98:99] offset:3072
	s_waitcnt vmcnt(0)
	ds_write_b128 v251, v[238:241]
	ds_write_b128 v251, v[242:245] offset:1024
	ds_write_b128 v251, v[246:249] offset:2048
	ds_write_b128 v251, v[206:209] offset:3072
	s_nop 1
	global_load_dwordx4 v[238:241], v96, s[100:101]
	global_load_dwordx4 v[242:245], v96, s[100:101] offset:1024
	global_load_dwordx4 v[246:249], v96, s[100:101] offset:2048
	global_load_dwordx4 v[206:209], v96, s[100:101] offset:3072
	s_waitcnt vmcnt(0)
	ds_write_b128 v251, v[238:241] offset:4096
	ds_write_b128 v251, v[242:245] offset:5120
	ds_write_b128 v251, v[246:249] offset:6144
	ds_write_b128 v251, v[206:209] offset:7168
	s_waitcnt lgkmcnt(0)
.Lrows_lds_skip:
	s_branch .LBB0_487

; __device__ __forceinline__ void phase_rows(const Ctx& c, int l) {
;     ...
;         for (int q = 0; q < 2; ++q) { const int mr = min(m0 + q * NGW, MTOK - 1); const f32x4* xr = (const f32x4*)(src + (size_t)mr * DM) + lane;
; #pragma unroll
;             for (int j = 0; j < 4; ++j) v[q][j] = xr[64 * j]; }
; #pragma unroll
;         for (int q = 0; q < 2; ++q) {
;         const int m = m0 + q * NGW;
;         if (m >= MTOK) continue;
;         if (l > 0) {
;             float s = 0.f;
; #pragma unroll
;             for (int j = 0; j < 4; ++j) s += (v[q][j].x + v[q][j].y) + (v[q][j].z + v[q][j].w);
;             const float mean = wave_sum(s) * (1.f / DM); float s2 = 0.f;
; #pragma unroll
;             for (int j = 0; j < 4; ++j) { v[q][j] = v[q][j] - mean; s2 += (v[q][j].x * v[q][j].x + v[q][j].y * v[q][j].y) + (v[q][j].z * v[q][j].z + v[q][j].w * v[q][j].w); }
;             const float rstd = 1.f / sqrtf(wave_sum(s2) * (1.f / DM) + LN_EPS);
;             const f32x4* gp = (const f32x4*)(c.inp(IN_LNG) + (size_t)(l - 1) * DM) + lane; const f32x4* bp = (const f32x4*)(c.inp(IN_LNB) + (size_t)(l - 1) * DM) + lane;
;             f32x4* orow = (f32x4*)(c.out + (size_t)m * DM) + lane;
; #pragma unroll
;             for (int j = 0; j < 4; ++j) { v[q][j] = v[q][j] * rstd * gp[64 * j] + bp[64 * j]; if (l == NLAYER) orow[64 * j] = v[q][j]; }
.LBB0_487:
	s_add_i32 s54, s46, s26
	s_ashr_i32 s47, s46, 31
	s_min_i32 s16, s54, 0x7fff
	s_lshl_b64 s[60:61], s[46:47], 12
	s_ashr_i32 s17, s16, 31
	s_waitcnt vmcnt(0)
	v_lshl_add_u64 v[138:139], v[174:175], 0, s[60:61]
	s_lshl_b64 s[16:17], s[16:17], 12
	global_load_dwordx4 v[166:169], v[138:139], off nt
	global_load_dwordx4 v[162:165], v[138:139], off offset:1024 nt
	global_load_dwordx4 v[158:161], v[138:139], off offset:2048 nt
	global_load_dwordx4 v[154:157], v[138:139], off offset:3072 nt
	v_lshl_add_u64 v[138:139], v[174:175], 0, s[16:17]
	global_load_dwordx4 v[150:153], v[138:139], off nt
	global_load_dwordx4 v[146:149], v[138:139], off offset:1024 nt
	global_load_dwordx4 v[142:145], v[138:139], off offset:2048 nt
	s_nop 0
	global_load_dwordx4 v[138:141], v[138:139], off offset:3072 nt
	v_cndmask_b32_e64 v96, 0, 1, s[48:49]
	v_cmp_ne_u32_e64 s[42:43], 1, v96
	s_andn2_b64 vcc, exec, s[48:49]
	s_cbranch_vccnz .LBB0_500
	s_waitcnt vmcnt(0)
	v_mov_b32_e32 v170, v167
	v_mov_b32_e32 v171, v168
	v_mov_b32_e32 v172, v166
	v_mov_b32_e32 v173, v169
	v_pk_add_f32 v[170:171], v[170:171], v[172:173]
	v_mov_b32_e32 v172, v163
	v_mov_b32_e32 v173, v164
	v_mov_b32_e32 v180, v162
	v_mov_b32_e32 v181, v165
	v_pk_add_f32 v[172:173], v[172:173], v[180:181]
	v_add_f32_e32 v96, v170, v171
	v_pk_add_f32 v[172:173], v[172:173], v[172:173] op_sel:[0,1] op_sel_hi:[1,0]
	v_add_f32_e32 v170, 0, v96
	v_add_f32_e32 v180, v158, v159
	v_add_f32_e32 v182, v160, v161
	v_mov_b32_e32 v171, v154
	v_mov_b32_e32 v173, v155
	v_mov_b32_e32 v181, v156
	v_mov_b32_e32 v183, v157
	v_pk_add_f32 v[170:171], v[170:171], v[172:173]
	v_pk_add_f32 v[172:173], v[180:181], v[182:183]
	s_load_dwordx4 s[64:67], s[12:13], 0x98
	v_pk_add_f32 v[170:171], v[170:171], v[172:173]
	v_lshl_add_u64 v[184:185], v[178:179], 0, s[60:61]
	v_add_f32_e32 v96, v170, v171
	s_nop 1
	v_add_f32_dpp v96, v96, v96 quad_perm:[1,0,3,2] row_mask:0xf bank_mask:0xf bound_ctrl:1
	s_nop 1
	v_add_f32_dpp v96, v96, v96 quad_perm:[2,3,0,1] row_mask:0xf bank_mask:0xf bound_ctrl:1
	s_nop 1
	v_add_f32_dpp v96, v96, v96 row_half_mirror row_mask:0xf bank_mask:0xf bound_ctrl:1
	s_nop 1
	v_add_f32_dpp v96, v96, v96 row_mirror row_mask:0xf bank_mask:0xf bound_ctrl:1
	s_nop 0
	v_readlane_b32 s0, v96, 16
	v_readlane_b32 s6, v96, 48
	v_readlane_b32 s16, v96, 0
	v_readlane_b32 s17, v96, 32
	v_mov_b32_e32 v170, s0
	v_mov_b32_e32 v171, s6
	v_pk_add_f32 v[170:171], s[16:17], v[170:171]
	s_nop 0
	v_add_f32_e32 v96, v170, v171
	v_fmamk_f32 v167, v96, 0xba800000, v167
	v_fmamk_f32 v166, v96, 0xba800000, v166
	v_fmamk_f32 v169, v96, 0xba800000, v169
	v_fmac_f32_e32 v168, 0xba800000, v96
	v_pk_mul_f32 v[170:171], v[168:169], v[168:169]
	v_pk_mul_f32 v[172:173], v[166:167], v[166:167]
	v_fmamk_f32 v183, v96, 0xba800000, v165
	v_pk_mov_b32 v[180:181], v[172:173], v[170:171] op_sel:[1,0]
	v_mov_b32_e32 v173, v171
	v_fmamk_f32 v182, v96, 0xba800000, v164
	v_fmamk_f32 v163, v96, 0xba800000, v163
	v_fmac_f32_e32 v162, 0xba800000, v96
	v_pk_add_f32 v[170:171], v[180:181], v[172:173]
	v_pk_mul_f32 v[164:165], v[182:183], v[182:183]
	v_pk_mul_f32 v[172:173], v[162:163], v[162:163]
	v_fmac_f32_e32 v158, 0xba800000, v96
	v_pk_mov_b32 v[180:181], v[172:173], v[164:165] op_sel:[1,0]
	v_mov_b32_e32 v173, v165
	v_pk_add_f32 v[164:165], v[180:181], v[172:173]
	v_fmamk_f32 v160, v96, 0xba800000, v160
	v_pk_add_f32 v[164:165], v[164:165], v[164:165] op_sel_hi:[0,1]
	v_fmamk_f32 v159, v96, 0xba800000, v159
	v_mul_f32_e32 v164, v158, v158
	v_fmamk_f32 v161, v96, 0xba800000, v161
	v_pk_fma_f32 v[172:173], v[158:159], v[158:159], v[164:165] op_sel_hi:[1,1,0]
	v_mul_f32_e32 v164, v160, v160
	v_pk_add_f32 v[170:171], v[170:171], v[170:171] op_sel_hi:[0,1]
	v_pk_fma_f32 v[180:181], v[160:161], v[160:161], v[164:165] op_sel_hi:[1,1,0]
	v_fmamk_f32 v157, v96, 0xba800000, v157
	v_fmamk_f32 v156, v96, 0xba800000, v156
	v_fmamk_f32 v155, v96, 0xba800000, v155
	v_fmac_f32_e32 v154, 0xba800000, v96
	v_mul_f32_e32 v172, v154, v154
	v_mul_f32_e32 v180, v155, v155
	v_mul_f32_e32 v170, v156, v156
	v_mul_f32_e32 v164, v157, v157
	v_pk_add_f32 v[172:173], v[172:173], v[180:181]
	v_pk_add_f32 v[164:165], v[170:171], v[164:165]
	s_nop 0
	v_pk_add_f32 v[164:165], v[172:173], v[164:165]
	s_nop 0
	v_add_f32_e32 v164, v164, v165
	s_nop 1
	v_add_f32_dpp v164, v164, v164 quad_perm:[1,0,3,2] row_mask:0xf bank_mask:0xf bound_ctrl:1
	s_nop 1
	v_add_f32_dpp v164, v164, v164 quad_perm:[2,3,0,1] row_mask:0xf bank_mask:0xf bound_ctrl:1
	s_nop 1
	v_add_f32_dpp v164, v164, v164 row_half_mirror row_mask:0xf bank_mask:0xf bound_ctrl:1
	s_nop 1
	v_add_f32_dpp v164, v164, v164 row_mirror row_mask:0xf bank_mask:0xf bound_ctrl:1
	s_nop 0
	v_readlane_b32 s0, v164, 16
	v_readlane_b32 s6, v164, 48
	v_readlane_b32 s16, v164, 0
	v_readlane_b32 s17, v164, 32
	v_mov_b32_e32 v164, s0
	v_mov_b32_e32 v165, s6
	v_pk_add_f32 v[164:165], s[16:17], v[164:165]
	s_nop 0
	v_add_f32_e32 v164, v164, v165
	v_fmamk_f32 v164, v164, 0x3a800000, v219
	v_cmp_gt_f32_e32 vcc, s87, v164
	v_mul_f32_e32 v165, 0x4f800000, v164
	s_nop 0
	v_cndmask_b32_e32 v164, v164, v165, vcc
	v_sqrt_f32_e32 v165, v164
	s_nop 0
	v_add_u32_e32 v170, -1, v165
	v_fma_f32 v171, -v170, v165, v164
	v_cmp_ge_f32_e64 s[40:41], 0, v171
	v_add_u32_e32 v171, 1, v165
	s_nop 0
	v_cndmask_b32_e64 v170, v165, v170, s[40:41]
	v_fma_f32 v165, -v171, v165, v164
	v_cmp_lt_f32_e64 s[40:41], 0, v165
	s_nop 1
	v_cndmask_b32_e64 v165, v170, v171, s[40:41]
	v_mul_f32_e32 v170, 0x37800000, v165
	v_cndmask_b32_e32 v165, v165, v170, vcc
	v_cmp_class_f32_e32 vcc, v164, v213
	s_nop 1
	v_cndmask_b32_e32 v164, v165, v164, vcc
	v_div_scale_f32 v165, s[16:17], v164, v164, 1.0
	v_rcp_f32_e32 v170, v165
	s_lshl_b64 s[16:17], s[22:23], 2
	s_waitcnt lgkmcnt(0)
	s_add_u32 s20, s64, s16
	s_addc_u32 s21, s65, s17
	v_fma_f32 v171, -v165, v170, 1.0
	v_fmac_f32_e32 v170, v171, v170
	v_div_scale_f32 v171, vcc, 1.0, v164, 1.0
	v_mul_f32_e32 v172, v171, v170
	v_fma_f32 v173, -v165, v172, v171
	v_fmac_f32_e32 v172, v173, v170
	v_fma_f32 v165, -v165, v172, v171
	v_div_fmas_f32 v165, v165, v170, v172
	v_div_fixup_f32 v180, v165, v164, 1.0
	v_lshlrev_b64 v[164:165], 4, v[200:201]
	s_add_u32 s16, s66, s16
	v_lshl_add_u64 v[186:187], s[20:21], 0, v[164:165]
	s_addc_u32 s17, s67, s17
	v_lshl_add_u64 v[188:189], s[16:17], 0, v[164:165]
	v_pk_mul_f32 v[190:191], v[166:167], v[180:181] op_sel_hi:[1,0]
	ds_read_b128 v[164:167], v251
	ds_read_b128 v[170:173], v251 offset:4096
	v_pk_mul_f32 v[168:169], v[168:169], v[180:181] op_sel_hi:[1,0]
	s_andn2_b64 vcc, exec, s[50:51]
	s_waitcnt lgkmcnt(0)
	v_pk_fma_f32 v[168:169], v[166:167], v[168:169], v[172:173]
	v_pk_fma_f32 v[166:167], v[164:165], v[190:191], v[170:171]
	v_cndmask_b32_e64 v164, 0, 1, s[50:51]
	v_cmp_ne_u32_e64 s[40:41], 1, v164
	s_cbranch_vccnz .LBB0_490
	global_store_dwordx4 v[184:185], v[166:169], off
; __device__ __forceinline__ void phase_rows(const Ctx& c, int l) {
;     ...
;             for (int j = 0; j < 4; ++j) { v[q][j] = v[q][j] * rstd * gp[64 * j] + bp[64 * j]; if (l == NLAYER) orow[64 * j] = v[q][j]; }
.LBB0_490:
	ds_read_b128 v[190:193], v251 offset:1024
	ds_read_b128 v[202:205], v251 offset:5120
	v_mov_b32_e32 v181, v180
	v_mov_b32_e32 v170, v180
	v_mov_b32_e32 v171, v180
	v_pk_mul_f32 v[164:165], v[182:183], v[170:171]
	v_pk_mul_f32 v[162:163], v[162:163], v[180:181]
	s_and_b64 vcc, exec, s[40:41]
	s_waitcnt lgkmcnt(0)
	v_pk_fma_f32 v[164:165], v[164:165], v[192:193], v[204:205]
	v_pk_fma_f32 v[162:163], v[162:163], v[190:191], v[202:203]
	s_cbranch_vccnz .LBB0_492
	global_store_dwordx4 v[184:185], v[162:165], off offset:1024
.LBB0_492:
	v_pk_mul_f32 v[182:183], v[160:161], v[170:171]
	v_pk_mul_f32 v[190:191], v[158:159], v[180:181]
	ds_read_b128 v[158:161], v251 offset:2048
	ds_read_b128 v[170:173], v251 offset:6144
	s_and_b64 vcc, exec, s[40:41]
	s_waitcnt lgkmcnt(0)
	v_pk_fma_f32 v[160:161], v[182:183], v[160:161], v[172:173]
	v_pk_fma_f32 v[158:159], v[190:191], v[158:159], v[170:171]
	s_cbranch_vccnz .LBB0_494
	global_store_dwordx4 v[184:185], v[158:161], off offset:2048
.LBB0_494:
	v_mov_b32_e32 v170, v180
	v_mov_b32_e32 v171, v180
	v_pk_mul_f32 v[182:183], v[156:157], v[170:171]
	v_pk_mul_f32 v[190:191], v[154:155], v[180:181]
	ds_read_b128 v[154:157], v251 offset:3072
	ds_read_b128 v[170:173], v251 offset:7168
	s_and_b64 vcc, exec, s[40:41]
	s_waitcnt lgkmcnt(0)
	v_pk_fma_f32 v[156:157], v[182:183], v[156:157], v[172:173]
	v_pk_fma_f32 v[154:155], v[190:191], v[154:155], v[170:171]
	s_cbranch_vccnz .LBB0_496
	global_store_dwordx4 v[184:185], v[154:157], off offset:3072

; __device__ __forceinline__ void phase_rows(const Ctx& c, int l) {
;     ...
;         if (l > 0) {
;             float s = 0.f;
; #pragma unroll
;             for (int j = 0; j < 4; ++j) s += (v[q][j].x + v[q][j].y) + (v[q][j].z + v[q][j].w);
;             const float mean = wave_sum(s) * (1.f / DM); float s2 = 0.f;
; #pragma unroll
;             for (int j = 0; j < 4; ++j) { v[q][j] = v[q][j] - mean; s2 += (v[q][j].x * v[q][j].x + v[q][j].y * v[q][j].y) + (v[q][j].z * v[q][j].z + v[q][j].w * v[q][j].w); }
;             const float rstd = 1.f / sqrtf(wave_sum(s2) * (1.f / DM) + LN_EPS);
;             const f32x4* gp = (const f32x4*)(c.inp(IN_LNG) + (size_t)(l - 1) * DM) + lane; const f32x4* bp = (const f32x4*)(c.inp(IN_LNB) + (size_t)(l - 1) * DM) + lane;
;             f32x4* orow = (f32x4*)(c.out + (size_t)m * DM) + lane;
; #pragma unroll
;             for (int j = 0; j < 4; ++j) { v[q][j] = v[q][j] * rstd * gp[64 * j] + bp[64 * j]; if (l == NLAYER) orow[64 * j] = v[q][j]; }
.LBB0_504:
	s_and_b64 vcc, exec, s[42:43]
	s_cbranch_vccnz .LBB0_516
	s_waitcnt vmcnt(0)
	v_mov_b32_e32 v154, v151
	v_mov_b32_e32 v155, v152
	v_mov_b32_e32 v156, v150
	v_mov_b32_e32 v157, v153
	v_pk_add_f32 v[154:155], v[154:155], v[156:157]
	v_mov_b32_e32 v156, v147
	v_mov_b32_e32 v157, v148
	v_mov_b32_e32 v158, v146
	v_mov_b32_e32 v159, v149
	v_pk_add_f32 v[156:157], v[156:157], v[158:159]
	v_add_f32_e32 v96, v154, v155
	v_pk_add_f32 v[156:157], v[156:157], v[156:157] op_sel:[0,1] op_sel_hi:[1,0]
	v_add_f32_e32 v154, 0, v96
	v_add_f32_e32 v158, v142, v143
	v_add_f32_e32 v160, v144, v145
	v_mov_b32_e32 v155, v138
	v_mov_b32_e32 v157, v139
	v_mov_b32_e32 v159, v140
	v_mov_b32_e32 v161, v141
	v_pk_add_f32 v[154:155], v[154:155], v[156:157]
	v_pk_add_f32 v[156:157], v[158:159], v[160:161]
	s_load_dwordx4 s[60:63], s[12:13], 0x98
	v_pk_add_f32 v[154:155], v[154:155], v[156:157]
	s_nop 0
	v_add_f32_e32 v96, v154, v155
	s_nop 1
	v_add_f32_dpp v96, v96, v96 quad_perm:[1,0,3,2] row_mask:0xf bank_mask:0xf bound_ctrl:1
	s_nop 1
	v_add_f32_dpp v96, v96, v96 quad_perm:[2,3,0,1] row_mask:0xf bank_mask:0xf bound_ctrl:1
	s_nop 1
	v_add_f32_dpp v96, v96, v96 row_half_mirror row_mask:0xf bank_mask:0xf bound_ctrl:1
	s_nop 1
	v_add_f32_dpp v96, v96, v96 row_mirror row_mask:0xf bank_mask:0xf bound_ctrl:1
	s_nop 0
	v_readlane_b32 s0, v96, 16
	v_readlane_b32 s6, v96, 48
	v_readlane_b32 s16, v96, 0
	v_readlane_b32 s17, v96, 32
	v_mov_b32_e32 v154, s0
	v_mov_b32_e32 v155, s6
	v_pk_add_f32 v[154:155], s[16:17], v[154:155]
	s_nop 0
	v_add_f32_e32 v96, v154, v155
	v_fmamk_f32 v151, v96, 0xba800000, v151
	v_fmamk_f32 v150, v96, 0xba800000, v150
	v_fmamk_f32 v153, v96, 0xba800000, v153
	v_fmac_f32_e32 v152, 0xba800000, v96
	v_pk_mul_f32 v[154:155], v[152:153], v[152:153]
	v_pk_mul_f32 v[156:157], v[150:151], v[150:151]
	v_fmamk_f32 v161, v96, 0xba800000, v149
	v_pk_mov_b32 v[158:159], v[156:157], v[154:155] op_sel:[1,0]
	v_mov_b32_e32 v157, v155
	v_fmamk_f32 v160, v96, 0xba800000, v148
	v_fmamk_f32 v147, v96, 0xba800000, v147
	v_fmac_f32_e32 v146, 0xba800000, v96
	v_pk_add_f32 v[154:155], v[158:159], v[156:157]
	v_pk_mul_f32 v[148:149], v[160:161], v[160:161]
	v_pk_mul_f32 v[156:157], v[146:147], v[146:147]
	v_fmac_f32_e32 v142, 0xba800000, v96
	v_pk_mov_b32 v[158:159], v[156:157], v[148:149] op_sel:[1,0]
	v_mov_b32_e32 v157, v149
	v_pk_add_f32 v[148:149], v[158:159], v[156:157]
	v_fmamk_f32 v144, v96, 0xba800000, v144
	v_pk_add_f32 v[148:149], v[148:149], v[148:149] op_sel_hi:[0,1]
	v_fmamk_f32 v143, v96, 0xba800000, v143
	v_mul_f32_e32 v148, v142, v142
	v_fmamk_f32 v145, v96, 0xba800000, v145
	v_pk_fma_f32 v[156:157], v[142:143], v[142:143], v[148:149] op_sel_hi:[1,1,0]
	v_mul_f32_e32 v148, v144, v144
	v_pk_add_f32 v[154:155], v[154:155], v[154:155] op_sel_hi:[0,1]
	v_pk_fma_f32 v[158:159], v[144:145], v[144:145], v[148:149] op_sel_hi:[1,1,0]
	v_fmamk_f32 v141, v96, 0xba800000, v141
	v_fmamk_f32 v140, v96, 0xba800000, v140
	v_fmamk_f32 v139, v96, 0xba800000, v139
	v_fmac_f32_e32 v138, 0xba800000, v96
	v_mul_f32_e32 v156, v138, v138
	v_mul_f32_e32 v158, v139, v139
	v_mul_f32_e32 v154, v140, v140
	v_mul_f32_e32 v148, v141, v141
	v_pk_add_f32 v[156:157], v[156:157], v[158:159]
	v_pk_add_f32 v[148:149], v[154:155], v[148:149]
	s_nop 0
	v_pk_add_f32 v[148:149], v[156:157], v[148:149]
	s_nop 0
	v_add_f32_e32 v148, v148, v149
	s_nop 1
	v_add_f32_dpp v148, v148, v148 quad_perm:[1,0,3,2] row_mask:0xf bank_mask:0xf bound_ctrl:1
	s_nop 1
	v_add_f32_dpp v148, v148, v148 quad_perm:[2,3,0,1] row_mask:0xf bank_mask:0xf bound_ctrl:1
	s_nop 1
	v_add_f32_dpp v148, v148, v148 row_half_mirror row_mask:0xf bank_mask:0xf bound_ctrl:1
	s_nop 1
	v_add_f32_dpp v148, v148, v148 row_mirror row_mask:0xf bank_mask:0xf bound_ctrl:1
	s_nop 0
	v_readlane_b32 s0, v148, 16
	v_readlane_b32 s6, v148, 48
	v_readlane_b32 s16, v148, 0
	v_readlane_b32 s17, v148, 32
	v_mov_b32_e32 v148, s0
	v_mov_b32_e32 v149, s6
	v_pk_add_f32 v[148:149], s[16:17], v[148:149]
	s_nop 0
	v_add_f32_e32 v148, v148, v149
	v_fmamk_f32 v148, v148, 0x3a800000, v219
	v_cmp_gt_f32_e32 vcc, s87, v148
	v_mul_f32_e32 v149, 0x4f800000, v148
	s_nop 0
	v_cndmask_b32_e32 v148, v148, v149, vcc
	v_sqrt_f32_e32 v149, v148
	s_nop 0
	v_add_u32_e32 v154, -1, v149
	v_fma_f32 v155, -v154, v149, v148
	v_cmp_ge_f32_e64 s[42:43], 0, v155
	v_add_u32_e32 v155, 1, v149
	s_nop 0
	v_cndmask_b32_e64 v154, v149, v154, s[42:43]
	v_fma_f32 v149, -v155, v149, v148
	v_cmp_lt_f32_e64 s[42:43], 0, v149
	s_nop 1
	v_cndmask_b32_e64 v149, v154, v155, s[42:43]
	v_mul_f32_e32 v154, 0x37800000, v149
	v_cndmask_b32_e32 v149, v149, v154, vcc
	v_cmp_class_f32_e32 vcc, v148, v213
	s_nop 1
	v_cndmask_b32_e32 v148, v149, v148, vcc
	v_div_scale_f32 v149, s[16:17], v148, v148, 1.0
	v_rcp_f32_e32 v154, v149
	s_lshl_b64 s[16:17], s[22:23], 2
	s_waitcnt lgkmcnt(0)
	s_add_u32 s20, s60, s16
	s_addc_u32 s21, s61, s17
	v_fma_f32 v155, -v149, v154, 1.0
	v_fmac_f32_e32 v154, v155, v154
	v_div_scale_f32 v155, vcc, 1.0, v148, 1.0
	v_mul_f32_e32 v156, v155, v154
	v_fma_f32 v157, -v149, v156, v155
	v_fmac_f32_e32 v156, v157, v154
	v_fma_f32 v149, -v149, v156, v155
	v_div_fmas_f32 v149, v149, v154, v156
	v_div_fixup_f32 v158, v149, v148, 1.0
	v_lshlrev_b64 v[148:149], 4, v[200:201]
	s_add_u32 s16, s62, s16
	v_lshl_add_u64 v[164:165], s[20:21], 0, v[148:149]
	s_addc_u32 s17, s63, s17
	v_lshl_add_u64 v[166:167], s[16:17], 0, v[148:149]
	v_pk_mul_f32 v[168:169], v[150:151], v[158:159] op_sel_hi:[1,0]
	ds_read_b128 v[148:151], v251
	ds_read_b128 v[154:157], v251 offset:4096
	s_ashr_i32 s55, s54, 31
	v_pk_mul_f32 v[152:153], v[152:153], v[158:159] op_sel_hi:[1,0]
	s_lshl_b64 s[16:17], s[54:55], 12
	v_lshl_add_u64 v[162:163], v[178:179], 0, s[16:17]
	s_andn2_b64 vcc, exec, s[50:51]
	s_waitcnt lgkmcnt(0)
	v_pk_fma_f32 v[152:153], v[150:151], v[152:153], v[156:157]
	v_pk_fma_f32 v[150:151], v[148:149], v[168:169], v[154:155]
	v_cndmask_b32_e64 v148, 0, 1, s[50:51]
	v_cmp_ne_u32_e64 s[42:43], 1, v148
	s_cbranch_vccnz .LBB0_507
	global_store_dwordx4 v[162:163], v[150:153], off
; __device__ __forceinline__ void phase_rows(const Ctx& c, int l) {
;     ...
;             for (int j = 0; j < 4; ++j) { v[q][j] = v[q][j] * rstd * gp[64 * j] + bp[64 * j]; if (l == NLAYER) orow[64 * j] = v[q][j]; }
.LBB0_507:
	ds_read_b128 v[168:171], v251 offset:1024
	ds_read_b128 v[180:183], v251 offset:5120
	v_mov_b32_e32 v159, v158
	v_mov_b32_e32 v154, v158
	v_mov_b32_e32 v155, v158
	v_pk_mul_f32 v[148:149], v[160:161], v[154:155]
	v_pk_mul_f32 v[146:147], v[146:147], v[158:159]
	s_and_b64 vcc, exec, s[42:43]
	s_waitcnt lgkmcnt(0)
	v_pk_fma_f32 v[148:149], v[148:149], v[170:171], v[182:183]
	v_pk_fma_f32 v[146:147], v[146:147], v[168:169], v[180:181]
	s_cbranch_vccnz .LBB0_509
	global_store_dwordx4 v[162:163], v[146:149], off offset:1024
.LBB0_509:
	v_pk_mul_f32 v[160:161], v[144:145], v[154:155]
	v_pk_mul_f32 v[168:169], v[142:143], v[158:159]
	ds_read_b128 v[142:145], v251 offset:2048
	ds_read_b128 v[154:157], v251 offset:6144
	s_and_b64 vcc, exec, s[42:43]
	s_waitcnt lgkmcnt(0)
	v_pk_fma_f32 v[144:145], v[160:161], v[144:145], v[156:157]
	v_pk_fma_f32 v[142:143], v[168:169], v[142:143], v[154:155]
	s_cbranch_vccnz .LBB0_511
	global_store_dwordx4 v[162:163], v[142:145], off offset:2048
.LBB0_511:
	v_mov_b32_e32 v154, v158
	v_mov_b32_e32 v155, v158
	v_pk_mul_f32 v[160:161], v[140:141], v[154:155]
	v_pk_mul_f32 v[168:169], v[138:139], v[158:159]
	ds_read_b128 v[138:141], v251 offset:3072
	ds_read_b128 v[154:157], v251 offset:7168
	s_and_b64 vcc, exec, s[42:43]
	s_waitcnt lgkmcnt(0)
	v_pk_fma_f32 v[140:141], v[160:161], v[140:141], v[156:157]
	v_pk_fma_f32 v[138:139], v[168:169], v[138:139], v[154:155]
	s_cbranch_vccnz .LBB0_513
	global_store_dwordx4 v[162:163], v[138:141], off offset:3072
